# work queues: a block leaves a phase after its first failing pop (no visits to other queues), all four queue-driven phases
# baseline (speedup 1.0000x reference)
.LBB0_198:
	s_or_b64 exec, exec, s[4:5]
	s_waitcnt lgkmcnt(0)
	s_barrier
	ds_read_b32 v0, v103
	s_movk_i32 s4, 0x1b0
	s_waitcnt lgkmcnt(0)
	v_cmp_gt_i32_e32 vcc, s4, v0
	v_readfirstlane_b32 s6, v0
	s_mov_b64 s[4:5], 0
	s_cbranch_vccnz .LBB0_201
	s_cmp_gt_i32 s47, -1
	s_cbranch_scc1 .LBB0_202
	s_add_i32 s4, s37, 1
	s_and_b32 s37, s4, 7
	s_add_i32 s47, s47, 1
	s_cbranch_execnz .LBB0_194
	s_branch .LBB0_203

.LBB0_610:
	s_or_b64 exec, exec, s[28:29]
	s_waitcnt lgkmcnt(0)
	s_barrier
	ds_read_b32 v0, v220
	s_movk_i32 s28, 0x120
	s_waitcnt lgkmcnt(0)
	v_cmp_gt_i32_e32 vcc, s28, v0
	v_readfirstlane_b32 s30, v0
	s_mov_b64 s[28:29], 0
	s_cbranch_vccnz .LBB0_613
	s_cmp_gt_i32 s63, -1
	s_cbranch_scc1 .LBB0_614
	s_add_i32 s28, s52, 1
	s_and_b32 s52, s28, 7
	s_add_i32 s63, s63, 1
	s_cbranch_execnz .LBB0_606
	s_branch .LBB0_615

.LBB0_814:
	s_or_b64 exec, exec, s[2:3]
	s_waitcnt lgkmcnt(0)
	s_barrier
	ds_read_b32 v0, v178
	s_movk_i32 s2, 0x100
	s_waitcnt lgkmcnt(0)
	v_cmp_gt_i32_e32 vcc, s2, v0
	v_readfirstlane_b32 s33, v0
	s_mov_b64 s[2:3], 0
	s_cbranch_vccnz .LBB0_817
	v_readlane_b32 s33, v248, 10
	s_cmp_gt_i32 s33, -1
	s_cbranch_scc1 .LBB0_818
	v_readlane_b32 s2, v248, 8
	s_add_i32 s2, s2, 1
	s_and_b32 s2, s2, 7
	v_writelane_b32 v248, s2, 8
	s_mov_b64 s[2:3], -1
	s_branch .LBB0_819

.LBB0_896:
	s_or_b64 exec, exec, s[8:9]
	s_waitcnt lgkmcnt(0)
	s_barrier
	ds_read_b32 v0, v105
	s_mov_b64 s[8:9], 0
	s_waitcnt lgkmcnt(0)
	v_cmp_gt_i32_e32 vcc, s15, v0
	v_readfirstlane_b32 s0, v0
	s_cbranch_vccnz .LBB0_899
	s_cmp_gt_i32 s20, -1
	s_cbranch_scc1 .LBB0_900
	s_add_i32 s0, s14, 1
	s_and_b32 s14, s0, 7
	s_add_i32 s20, s20, 1
	s_cbranch_execnz .LBB0_892
	s_branch .LBB0_901
